# selection sub-key tables stored in MFMA-fragment order (8 full lines per load instead of 16 half lines)
# speedup vs baseline: 1.2106x; 1.0097x over previous
; #define SK_LOAD(KF, P_) do { _Pragma("unroll") for (int t = 0; t < 2; ++t) _Pragma("unroll") for (int ks = 0; ks < 4; ++ks) KF[t][ks] = *(const bf16x8*)(kp0 + (size_t)(16 * (2 * (P_) + t)) * 128 + 32 * ks); } while (0)
; #define SK_MMA(KF, P_) do { _Pragma("unroll") for (int t = 0; t < 2; ++t) { st[2 * (P_) + t] = (f32x4){0.f, 0.f, 0.f, 0.f}; \
;                       _Pragma("unroll") for (int ks = 0; ks < 4; ++ks) st[2 * (P_) + t] = __builtin_amdgcn_mfma_f32_16x16x32_bf16(KF[t][ks], qf[ks], st[2 * (P_) + t], 0, 0, 0); } } while (0)
; __device__ __forceinline__ void peer_phase(const Ctx& C, const bf16* PQ, const bf16* SK  , const unsigned char* ED, const unsigned char* EU, const bf16* HB  , bf16* XBN  , float* RSS, float* xio, const float* gfinal, bool last, float* SELG, int* SELI) {
;     ...
;                   if (hh * 2 + c + 1 < 16) { const bf16* qp = PQ + (size_t)(tok0 + i) * 2048 + (hh * 2 + c + 1) * 128 + g * 8;
; #pragma unroll
;                       for (int ks = 0; ks < 4; ++ks) qn[ks] = __builtin_nontemporal_load((const bf16x8*)(qp + 32 * ks)); }
;                   bf16x8 kfA[2][4], kfB[2][4];
;                   const bf16* kp0 = SK + (size_t)(c * 128 + i) * 128 + 8 * g;
;     ...
;                   SK_LOAD(kfA, 0);
;                   SK_LOAD(kfB, 1); asm volatile("" ::: "memory");
;                   SK_MMA(kfA, 0); SK_LOAD(kfA, 2); asm volatile("" ::: "memory");
;                   SK_MMA(kfB, 1); SK_LOAD(kfB, 3); asm volatile("" ::: "memory");
;                   SK_MMA(kfA, 2); SK_MMA(kfB, 3);
.LBB0_157:
	v_mul_u32_u24_e32 v16, 0xf0, v85
	v_lshl_add_u32 v16, v84, 4, v16
	v_lshl_or_b32 v136, s93, 15, v16
	v_lshl_add_u64 v[82:83], v[74:75], 0, v[136:137]
	global_load_dwordx4 v[16:19], v[82:83], off
	global_load_dwordx4 v[20:23], v[82:83], off offset:1024
	global_load_dwordx4 v[130:133], v[82:83], off offset:2048
	global_load_dwordx4 v[142:145], v[82:83], off offset:3072
	v_add_co_u32_e32 v24, vcc, 0x1000, v82
	s_xor_b64 s[70:71], s[0:1], -1
	s_nop 0
	v_addc_co_u32_e32 v25, vcc, 0, v83, vcc
	s_movk_i32 s0, 0x2000
	v_add_co_u32_e32 v36, vcc, s0, v82
	s_movk_i32 s0, 0x3000
	s_nop 0
	v_addc_co_u32_e32 v37, vcc, 0, v83, vcc
	v_add_co_u32_e32 v68, vcc, s0, v82
	global_load_dwordx4 v[146:149], v[24:25], off
	global_load_dwordx4 v[150:153], v[24:25], off offset:1024
	global_load_dwordx4 v[154:157], v[24:25], off offset:2048
	global_load_dwordx4 v[158:161], v[24:25], off offset:3072
	v_addc_co_u32_e32 v69, vcc, 0, v83, vcc
	global_load_dwordx4 v[24:27], v[68:69], off offset:-4096
	global_load_dwordx4 v[28:31], v[36:37], off offset:1024
	global_load_dwordx4 v[32:35], v[36:37], off offset:2048
	s_nop 0
	global_load_dwordx4 v[36:39], v[36:37], off offset:3072
	s_nop 0
	global_load_dwordx4 v[44:47], v[68:69], off
	global_load_dwordx4 v[60:63], v[68:69], off offset:1024
	global_load_dwordx4 v[64:67], v[68:69], off offset:2048
	s_nop 0
	global_load_dwordx4 v[68:71], v[68:69], off offset:3072
	s_movk_i32 s0, 0x4000
	v_add_co_u32_e32 v134, vcc, s0, v82
	s_movk_i32 s0, 0x5000
	s_nop 0
	v_addc_co_u32_e32 v135, vcc, 0, v83, vcc
	v_add_co_u32_e32 v166, vcc, s0, v82
	s_movk_i32 s0, 0x6000
	s_nop 0
	v_addc_co_u32_e32 v167, vcc, 0, v83, vcc
	s_mov_b32 s2, 0
	s_waitcnt vmcnt(15)
	v_mfma_f32_16x16x32_bf16 v[16:19], v[16:19], v[40:43], 0
	s_waitcnt vmcnt(14)
	v_mfma_f32_16x16x32_bf16 v[16:19], v[20:23], v[48:51], v[16:19]
	s_waitcnt vmcnt(13)
	v_mfma_f32_16x16x32_bf16 v[16:19], v[130:133], v[52:55], v[16:19]
	s_waitcnt vmcnt(7)
	v_mfma_f32_16x16x32_bf16 v[24:27], v[24:27], v[40:43], 0
	v_mfma_f32_16x16x32_bf16 v[20:23], v[142:145], v[56:59], v[16:19]
	v_mfma_f32_16x16x32_bf16 v[16:19], v[146:149], v[40:43], 0
	s_waitcnt vmcnt(6)
	v_mfma_f32_16x16x32_bf16 v[24:27], v[28:31], v[48:51], v[24:27]
	v_mfma_f32_16x16x32_bf16 v[16:19], v[150:153], v[48:51], v[16:19]
	s_waitcnt vmcnt(5)
	v_mfma_f32_16x16x32_bf16 v[24:27], v[32:35], v[52:55], v[24:27]
	v_add_co_u32_e32 v32, vcc, s0, v82
	s_movk_i32 s0, 0x7000
	v_mfma_f32_16x16x32_bf16 v[16:19], v[154:157], v[52:55], v[16:19]
	v_addc_co_u32_e32 v33, vcc, 0, v83, vcc
	v_add_co_u32_e32 v34, vcc, s0, v82
	s_waitcnt vmcnt(4)
	v_mfma_f32_16x16x32_bf16 v[28:31], v[36:39], v[56:59], v[24:27]
	v_addc_co_u32_e32 v35, vcc, 0, v83, vcc
	s_mov_b64 s[0:1], 0
	s_waitcnt vmcnt(3)
	v_mfma_f32_16x16x32_bf16 v[24:27], v[44:47], v[40:43], 0
	v_mfma_f32_16x16x32_bf16 v[16:19], v[158:161], v[56:59], v[16:19]
	global_load_dwordx4 v[130:133], v[166:167], off offset:-4096
	global_load_dwordx4 v[142:145], v[134:135], off offset:1024
	global_load_dwordx4 v[146:149], v[134:135], off offset:2048
	global_load_dwordx4 v[150:153], v[134:135], off offset:3072
	global_load_dwordx4 v[154:157], v[166:167], off
	global_load_dwordx4 v[158:161], v[166:167], off offset:1024
	global_load_dwordx4 v[162:165], v[166:167], off offset:2048
	s_nop 0
	global_load_dwordx4 v[166:169], v[166:167], off offset:3072
	s_waitcnt vmcnt(10)
	v_mfma_f32_16x16x32_bf16 v[24:27], v[60:63], v[48:51], v[24:27]
	s_waitcnt vmcnt(9)
	v_mfma_f32_16x16x32_bf16 v[24:27], v[64:67], v[52:55], v[24:27]
	s_waitcnt vmcnt(8)
; #define SK_LOAD(KF, P_) do { _Pragma("unroll") for (int t = 0; t < 2; ++t) _Pragma("unroll") for (int ks = 0; ks < 4; ++ks) KF[t][ks] = *(const bf16x8*)(kp0 + (size_t)(16 * (2 * (P_) + t)) * 128 + 32 * ks); } while (0)
; #define SK_MMA(KF, P_) do { _Pragma("unroll") for (int t = 0; t < 2; ++t) { st[2 * (P_) + t] = (f32x4){0.f, 0.f, 0.f, 0.f}; \
;                       _Pragma("unroll") for (int ks = 0; ks < 4; ++ks) st[2 * (P_) + t] = __builtin_amdgcn_mfma_f32_16x16x32_bf16(KF[t][ks], qf[ks], st[2 * (P_) + t], 0, 0, 0); } } while (0)
; __device__ __forceinline__ void peer_phase(const Ctx& C, const bf16* PQ, const bf16* SK  , const unsigned char* ED, const unsigned char* EU, const bf16* HB  , bf16* XBN  , float* RSS, float* xio, const float* gfinal, bool last, float* SELG, int* SELI) {
;     ...
;                   SK_MMA(kfA, 0); SK_LOAD(kfA, 2); asm volatile("" ::: "memory");
;                   SK_MMA(kfB, 1); SK_LOAD(kfB, 3); asm volatile("" ::: "memory");
;                   SK_MMA(kfA, 2); SK_MMA(kfB, 3);
;     ...
;                 }
;                 float lo, hi;
;                 { float mn = st[0][0], mx = st[0][0];
; #pragma unroll
;                   for (int kt = 0; kt < 8; ++kt)
; #pragma unroll
;                       for (int j = 0; j < 4; ++j) { mn = fminf(mn, st[kt][j]); mx = fmaxf(mx, st[kt][j]); }
;                   mn = fminf(mn, __shfl_xor(mn, 16)); mn = fminf(mn, __shfl_xor(mn, 32)); mx = fmaxf(mx, __shfl_xor(mx, 16)); mx = fmaxf(mx, __shfl_xor(mx, 32));
;                   lo = mn; hi = mx; }
	v_mfma_f32_16x16x32_bf16 v[24:27], v[68:71], v[56:59], v[24:27]
	global_load_dwordx4 v[44:47], v[34:35], off offset:-4096
	global_load_dwordx4 v[60:63], v[32:33], off offset:1024
	global_load_dwordx4 v[64:67], v[32:33], off offset:2048
	global_load_dwordx4 v[68:71], v[32:33], off offset:3072
	global_load_dwordx4 v[170:173], v[34:35], off
	global_load_dwordx4 v[190:193], v[34:35], off offset:1024
	global_load_dwordx4 v[194:197], v[34:35], off offset:2048
	global_load_dwordx4 v[198:201], v[34:35], off offset:3072
	s_waitcnt vmcnt(15)
	v_mfma_f32_16x16x32_bf16 v[32:35], v[130:133], v[40:43], 0
	s_waitcnt vmcnt(14)
	v_mfma_f32_16x16x32_bf16 v[32:35], v[142:145], v[48:51], v[32:35]
	s_waitcnt vmcnt(13)
	v_mfma_f32_16x16x32_bf16 v[32:35], v[146:149], v[52:55], v[32:35]
	s_waitcnt vmcnt(12)
	v_mfma_f32_16x16x32_bf16 v[36:39], v[150:153], v[56:59], v[32:35]
	s_waitcnt vmcnt(11)
	v_mfma_f32_16x16x32_bf16 v[32:35], v[154:157], v[40:43], 0
	s_waitcnt vmcnt(7)
	v_mfma_f32_16x16x32_bf16 v[44:47], v[44:47], v[40:43], 0
	s_waitcnt vmcnt(3)
	v_mfma_f32_16x16x32_bf16 v[40:43], v[170:173], v[40:43], 0
	v_mfma_f32_16x16x32_bf16 v[32:35], v[158:161], v[48:51], v[32:35]
	v_mfma_f32_16x16x32_bf16 v[44:47], v[60:63], v[48:51], v[44:47]
	s_waitcnt vmcnt(2)
	v_mfma_f32_16x16x32_bf16 v[40:43], v[190:193], v[48:51], v[40:43]
	v_max_f32_e32 v48, v21, v21
	v_max_f32_e32 v49, v20, v20
	v_min_f32_e32 v50, v49, v48
	v_max_f32_e32 v48, v49, v48
	v_max3_f32 v48, v48, v22, v23
	v_mfma_f32_16x16x32_bf16 v[32:35], v[162:165], v[52:55], v[32:35]
	v_max3_f32 v48, v48, v16, v17
	v_max3_f32 v48, v48, v18, v19
	v_min3_f32 v49, v50, v22, v23
	v_mfma_f32_16x16x32_bf16 v[44:47], v[64:67], v[52:55], v[44:47]
	v_max3_f32 v48, v48, v28, v29
	v_min3_f32 v49, v49, v16, v17
	v_max3_f32 v48, v48, v30, v31
	v_mfma_f32_16x16x32_bf16 v[32:35], v[166:169], v[56:59], v[32:35]
	v_min3_f32 v49, v49, v18, v19
	v_max3_f32 v48, v48, v24, v25
	v_min3_f32 v49, v49, v28, v29
	s_waitcnt vmcnt(1)
	v_mfma_f32_16x16x32_bf16 v[40:43], v[194:197], v[52:55], v[40:43]
	v_max3_f32 v48, v48, v26, v27
	v_min3_f32 v49, v49, v30, v31
	v_max3_f32 v48, v48, v36, v37
	v_mfma_f32_16x16x32_bf16 v[44:47], v[68:71], v[56:59], v[44:47]
	v_min3_f32 v49, v49, v24, v25
	v_max3_f32 v48, v48, v38, v39
	v_min3_f32 v49, v49, v26, v27
	s_waitcnt vmcnt(0)
	v_mfma_f32_16x16x32_bf16 v[40:43], v[198:201], v[56:59], v[40:43]
	v_max3_f32 v48, v48, v32, v33
	v_min3_f32 v49, v49, v36, v37
	v_max3_f32 v48, v48, v34, v35
	v_min3_f32 v49, v49, v38, v39
	v_max3_f32 v48, v48, v44, v45
	v_min3_f32 v49, v49, v32, v33
	v_max3_f32 v48, v48, v46, v47
	v_min3_f32 v49, v49, v34, v35
	v_max3_f32 v48, v48, v40, v41
	v_and_b32_e32 v50, 64, v181
	v_min3_f32 v49, v49, v44, v45
	v_max3_f32 v52, v48, v42, v43
	v_xor_b32_e32 v48, 16, v181
	v_add_u32_e32 v51, 64, v50
	v_min3_f32 v49, v49, v46, v47
	v_cmp_lt_i32_e32 vcc, v48, v51
	v_min3_f32 v49, v49, v40, v41
	v_min3_f32 v49, v49, v42, v43
	v_cndmask_b32_e32 v48, v181, v48, vcc
	v_lshlrev_b32_e32 v48, 2, v48
	ds_bpermute_b32 v53, v48, v49
	s_waitcnt lgkmcnt(0)
	v_max_f32_e32 v53, v53, v53
	v_min_f32_e32 v53, v49, v53
	v_xor_b32_e32 v49, 32, v181
	v_cmp_lt_i32_e32 vcc, v49, v51
	s_nop 1
	v_cndmask_b32_e32 v49, v181, v49, vcc
	v_lshlrev_b32_e32 v49, 2, v49
	ds_bpermute_b32 v51, v49, v53
	s_waitcnt lgkmcnt(0)
	v_max_f32_e32 v51, v51, v51
	v_min_f32_e32 v51, v53, v51
	ds_bpermute_b32 v53, v48, v52
	s_waitcnt lgkmcnt(0)
	v_max_f32_e32 v53, v53, v53
	v_max_f32_e32 v52, v52, v53
	ds_bpermute_b32 v53, v49, v52
	s_waitcnt lgkmcnt(0)
	v_max_f32_e32 v53, v53, v53
	v_max_f32_e32 v52, v52, v53
	s_mov_b64 s[4:5], 0
	s_mov_b32 s2, 0
	s_waitcnt lgkmcnt(0)

; __device__ __forceinline__ unsigned pk2(float lo, float hi) { return f2bf(lo) | (f2bf(hi) << 16); }
; __device__ __forceinline__ void cvt_bf16(const Ctx& C, const float* src, bf16* dst, size_t n) {
;     int lane = threadIdx.x & 63; asm volatile("" : "+v"(lane));
;     const size_t nth = (size_t)C.ngw * 64, n8 = n / 8;
;     for (size_t i = (size_t)C.gw * 64 + lane; i < n8; i += nth) {
;         const f32x4 a = *(const f32x4*)(src + i * 8), b = *(const f32x4*)(src + i * 8 + 4);
;         v4u o; o.x = pk2(a.x, a.y); o.y = pk2(a.z, a.w); o.z = pk2(b.x, b.y); o.w = pk2(b.z, b.w);
;         *(v4u*)(dst + i * 8) = o;
;     }
; }
.LBB0_277:
	s_or_saveexec_b64 s[0:1], s[0:1]
	v_readlane_b32 s12, v248, 62
	v_mov_b64_e32 v[2:3], s[8:9]
	v_readlane_b32 s13, v248, 63
	s_xor_b64 exec, exec, s[0:1]
	s_cbranch_execz .LBB0_281
	v_readlane_b32 s14, v247, 53
	v_readlane_b32 s15, v247, 54
	s_lshl_b64 s[8:9], s[14:15], 11
	v_readlane_b32 s2, v248, 44
	s_add_u32 s10, s2, s8
	v_readlane_b32 s2, v248, 61
	v_lshlrev_b64 v[2:3], 5, v[4:5]
	s_addc_u32 s11, s2, s9
	v_lshl_add_u64 v[2:3], s[10:11], 0, v[2:3]
	s_lshl_b64 s[10:11], s[14:15], 10
	v_readlane_b32 s2, v249, 18
	s_add_u32 s10, s2, s10
	v_readlane_b32 s2, v249, 19
	s_addc_u32 s11, s2, s11
	v_lshl_add_u64 v[4:5], v[4:5], 4, s[10:11]
	s_mov_b64 s[10:11], 0
	v_readlane_b32 s14, v249, 18
	v_readlane_b32 s15, v249, 19
.LBB0_279:
	s_waitcnt lgkmcnt(0)
	global_load_dwordx4 v[6:9], v[2:3], off offset:-16
	global_load_dwordx4 v[10:13], v[2:3], off
	v_lshl_add_u64 v[0:1], v[0:1], 0, s[36:37]
	v_cmp_lt_u64_e32 vcc, s[56:57], v[0:1]
	v_lshl_add_u64 v[2:3], v[2:3], 0, s[38:39]
	s_or_b64 s[10:11], vcc, s[10:11]
	s_waitcnt vmcnt(0)
	v_bfe_u32 v14, v6, 16, 1
	v_bfe_u32 v16, v8, 16, 1
	v_bfe_u32 v18, v10, 16, 1
	v_bfe_u32 v20, v12, 16, 1
	v_bfe_u32 v15, v7, 16, 1
	v_bfe_u32 v17, v9, 16, 1
	v_bfe_u32 v19, v11, 16, 1
	v_bfe_u32 v21, v13, 16, 1
	v_add3_u32 v6, v6, v14, s86
	v_add3_u32 v8, v8, v16, s86
	v_add3_u32 v10, v10, v18, s86
	v_add3_u32 v12, v12, v20, s86
	v_add3_u32 v7, v7, v15, s86
	v_add3_u32 v9, v9, v17, s86
	v_add3_u32 v11, v11, v19, s86
	v_add3_u32 v13, v13, v21, s86
	v_lshrrev_b32_e32 v6, 16, v6
	v_lshrrev_b32_e32 v8, 16, v8
	v_lshrrev_b32_e32 v10, 16, v10
	v_lshrrev_b32_e32 v12, 16, v12
	v_and_or_b32 v6, v7, s85, v6
	v_and_or_b32 v7, v9, s85, v8
	v_and_or_b32 v8, v11, s85, v10
	v_and_or_b32 v9, v13, s85, v12
	v_subrev_u32_e32 v22, s14, v4
	v_lshrrev_b32_e32 v22, 4, v22
	v_and_b32_e32 v23, 15, v22
	v_bfe_u32 v24, v22, 4, 4
	v_bfe_u32 v25, v22, 8, 3
	v_and_b32_e32 v26, 3, v23
	v_lshrrev_b32_e32 v23, 2, v23
	v_lshl_or_b32 v24, v26, 4, v24
	v_lshl_or_b32 v24, v23, 6, v24
	v_lshl_or_b32 v24, v25, 8, v24
	v_and_b32_e32 v22, 0xfffff800, v22
	v_or_b32_e32 v22, v22, v24
	v_lshlrev_b32_e32 v22, 4, v22
	v_mov_b32_e32 v23, 0
	v_lshl_add_u64 v[26:27], s[14:15], 0, v[22:23]
	global_store_dwordx4 v[26:27], v[6:9], off
	v_lshl_add_u64 v[4:5], v[4:5], 0, s[12:13]
	s_andn2_b64 exec, exec, s[10:11]
	s_cbranch_execnz .LBB0_279
	s_or_b64 exec, exec, s[10:11]
	v_mov_b64_e32 v[2:3], s[8:9]
